# GLA scan: state image packed with one v_cvt_pk_bf16_f32 per pair (was two conversions and a v_perm)
# speedup vs baseline: 1.0004x; 1.0004x over previous
; DI bf16x8 tr2(const bf16_t* p0, const bf16_t* p1) { s16x4 a = trread(p0), b = trread(p1); return __builtin_shufflevector(a, b, 0, 1, 2, 3, 4, 5, 6, 7); }
; DI f32x4 mfma16(bf16x8 a, bf16x8 b, f32x4 c) { return __builtin_amdgcn_mfma_f32_16x16x32_bf16(a, b, c, 0, 0, 0); }
; DI void gla_scan_item(const P& p, int seq, unsigned char* smem) {
;     ...
;     auto compute = [&](int c) {
;         const unsigned char* base = smem + (c & 1) * BUFB;
;         const bf16_t* sat = (const bf16_t*)base; const bf16_t* sqt = (const bf16_t*)(base + 2560); const bf16_t* sko = (const bf16_t*)(base + 2560 + 4608); const bf16_t* sv = (const bf16_t*)(base + 2560 + 9216); const float* sdc = (const float*)(base + 2560 + 9216 + 8704);
;         const int dv0 = 16 * w;
;         const bf16x8 vb = tr2(sv + (8 * g + q4) * 136 + dv0 + 4 * p4, sv + (8 * g + 4 + q4) * 136 + dv0 + 4 * p4);
;         bf16x8 bs[2];
;         bs[0] = packacc(st[0], st[1]); bs[1] = packacc(st[2], st[3]);
; #pragma unroll
;         for (int mt = 0; mt < 2; ++mt) {
;             f32x4 acc = (f32x4){0.f, 0.f, 0.f, 0.f};
;             acc = mfma16(vb, ld8(sat + (16 * mt + l15) * 40 + 8 * g), acc);
; #pragma unroll
;             for (int ks = 0; ks < 2; ++ks) {
;                 const bf16_t* r0 = sqt + (16 * mt + l15) * 72 + 32 * ks + 4 * g;
;                 acc = mfma16(bs[ks], ld4x2(r0, r0 + 16), acc);
;             }
;             bf16_t* ob = OG + (size_t)prow(b, dir, 32 * c) * 512 + 128 * h;
;             u32x2 ov; ov.x = pk2(acc[0], acc[1]); ov.y = pk2(acc[2], acc[3]);
;             *(u32x2*)(ob + sgn * ((16 * mt + l15) * 512) + dv0 + 4 * g) = ov;
;         }
; #pragma unroll
;         for (int dt = 0; dt < 4; ++dt) {
;             const bf16x8 ak = tr2(sko + (8 * g + q4) * 72 + 16 * dt + 4 * p4, sko + (8 * g + 4 + q4) * 72 + 16 * dt + 4 * p4);
; #pragma unroll
;             for (int r = 0; r < 4; ++r) st[dt][r] *= sdc[16 * dt + 4 * g + r];
;             st[dt] = mfma16(ak, vb, st[dt]);
;         }
;     };
.LBB0_579:
	ds_read_b64_tr_b16 v[200:201], v123 offset:32512
	ds_read_b64_tr_b16 v[202:203], v124 offset:32512
	ds_read_b128 v[204:207], v125 offset:20736
	ds_read2_b64 v[208:211], v159 offset0:96 offset1:100
	ds_read2_b64 v[212:215], v159 offset0:104 offset1:108
	ds_read2_b64 v[216:219], v162 offset0:96 offset1:100
	ds_read_b128 v[224:227], v127 offset:20736
	ds_read2_b64 v[228:231], v162 offset0:104 offset1:108
	ds_read2_b32 v[232:233], v163 offset1:1
	ds_read2_b32 v[234:235], v183 offset1:1
	ds_read_b64_tr_b16 v[238:239], v147 offset:27904
	ds_read_b64_tr_b16 v[242:243], v147 offset:27936
	v_cvt_pk_bf16_f32 v86, v72, v73
	v_cvt_pk_bf16_f32 v85, v94, v95
	v_cvt_pk_bf16_f32 v84, v92, v93
	v_cvt_pk_bf16_f32 v87, v74, v75
	s_waitcnt lgkmcnt(9)
	v_mfma_f32_16x16x32_bf16 v[76:79], v[200:203], v[204:207], 0
	ds_read_b64_tr_b16 v[236:237], v146 offset:27904
	ds_read_b64_tr_b16 v[240:241], v146 offset:27936
	ds_read2_b32 v[244:245], v185 offset1:1
	s_add_i32 s4, s26, 0x60
	s_add_i32 s5, s26, 0xffffff60
	s_add_i32 s6, s27, 0xfffff800
	s_and_b64 s[2:3], s[0:1], exec
	s_cselect_b32 s2, s4, s6
	s_waitcnt lgkmcnt(11)
	v_mfma_f32_16x16x32_bf16 v[76:79], v[84:87], v[208:211], v[76:79]
	ds_read2_b32 v[246:247], v184 offset1:1
	v_cvt_pk_bf16_f32 v152, v88, v89
	v_cvt_pk_bf16_f32 v151, v82, v83
	v_cvt_pk_bf16_f32 v150, v80, v81
	v_cvt_pk_bf16_f32 v153, v90, v91
	s_add_i32 s4, s2, s22
	s_and_b64 s[2:3], s[0:1], exec
	s_cselect_b32 s2, s5, s27
	s_add_i32 s2, s2, s21
	s_cmp_lt_u32 s24, 3
	s_waitcnt lgkmcnt(11)
	v_mfma_f32_16x16x32_bf16 v[76:79], v[150:153], v[212:215], v[76:79]
	ds_read_b64_tr_b16 v[248:249], v146 offset:27968
	s_cselect_b32 s2, s4, s2
	s_ashr_i32 s3, s2, 31
	s_lshl_b64 s[36:37], s[2:3], 10
	s_mov_b64 s[2:3], 0x3000
	s_nop 2
	v_cvt_pk_bf16_f32 v76, v76, v77
	v_cvt_pk_bf16_f32 v77, v78, v79
	v_lshl_add_u64 v[78:79], v[100:101], 0, s[36:37]
	global_store_dwordx2 v[78:79], v[76:77], off
	s_waitcnt lgkmcnt(10)
	v_mfma_f32_16x16x32_bf16 v[76:79], v[200:203], v[224:227], 0
	ds_read_b64_tr_b16 v[250:251], v147 offset:27968
	ds_read2_b32 v[204:205], v164 offset1:1
	v_lshl_add_u64 v[106:107], v[106:107], 0, s[2:3]
	s_mov_b64 s[2:3], 0x6000
	s_addk_i32 s26, 0xc0
	v_mfma_f32_16x16x32_bf16 v[76:79], v[84:87], v[216:219], v[76:79]
	v_lshl_add_u64 v[108:109], v[108:109], 0, s[2:3]
	s_addk_i32 s27, 0xff40
	s_waitcnt lgkmcnt(11)
	v_mfma_f32_16x16x32_bf16 v[76:79], v[150:153], v[228:231], v[76:79]
	ds_read2_b32 v[206:207], v165 offset1:1
	s_mov_b64 s[2:3], 0x600
	v_lshl_add_u64 v[110:111], v[110:111], 0, s[2:3]
	s_cmpk_lt_u32 s24, 0x42
	s_nop 4
	v_cvt_pk_bf16_f32 v76, v76, v77
	v_cvt_pk_bf16_f32 v77, v78, v79
	v_lshl_add_u64 v[78:79], v[102:103], 0, s[36:37]
	global_store_dwordx2 v[78:79], v[76:77], off
	s_waitcnt lgkmcnt(11)
	v_pk_mul_f32 v[76:77], v[92:93], v[232:233]
	ds_read_b64_tr_b16 v[208:209], v146 offset:28000
	s_waitcnt lgkmcnt(11)
	v_pk_mul_f32 v[78:79], v[94:95], v[234:235]
	ds_read_b64_tr_b16 v[210:211], v147 offset:28000
	s_waitcnt lgkmcnt(9)
	v_mfma_f32_16x16x32_bf16 v[84:87], v[236:239], v[200:203], v[76:79]
	ds_read2_b32 v[212:213], v187 offset1:1
	ds_read2_b32 v[214:215], v186 offset1:1
	s_nop 2
	s_waitcnt lgkmcnt(9)
	v_pk_mul_f32 v[72:73], v[72:73], v[244:245]
	s_waitcnt lgkmcnt(8)
	v_pk_mul_f32 v[74:75], v[74:75], v[246:247]
	s_nop 1
	v_mfma_f32_16x16x32_bf16 v[76:79], v[240:243], v[200:203], v[72:75]
	s_nop 2
	s_waitcnt lgkmcnt(5)
	v_pk_mul_f32 v[80:81], v[80:81], v[204:205]
	s_waitcnt lgkmcnt(4)
	v_pk_mul_f32 v[82:83], v[82:83], v[206:207]
	s_nop 1
	v_mfma_f32_16x16x32_bf16 v[80:83], v[248:251], v[200:203], v[80:83]
	s_waitcnt lgkmcnt(1)
	v_pk_mul_f32 v[88:89], v[88:89], v[212:213]
	s_waitcnt lgkmcnt(0)
	v_pk_mul_f32 v[90:91], v[90:91], v[214:215]
	s_nop 1
	v_mfma_f32_16x16x32_bf16 v[72:75], v[208:211], v[200:203], v[88:91]
	s_cbranch_scc0 .LBB0_639

; DI void gla_scan_item(const P& p, int seq, unsigned char* smem) {
;     ...
;     auto loadr = [&](GlaRegs& R, int c) {
;         if (c >= 72) return;
;         { const int pos = tid >> 4, ch = tid & 15; R.rv = *(const u32x4*)(S + (size_t)prow(b, dir, 32 * c + pos) * NP + C_GLA_V + 128 * h + 8 * ch); }
;         { const int t2 = tid & 255, pos = t2 >> 3, ch = t2 & 7; const bf16_t* src = (tid < 256 ? QT : KO) + ((size_t)seq * PT + 32 * c + pos) * 64 + 8 * ch; R.rq = __builtin_nontemporal_load((const u32x4*)src); }
;         if (tid < 128) { const int i = tid >> 2, ch = tid & 3; R.ra = __builtin_nontemporal_load((const u32x4*)(AT + (((size_t)seq * 72 + c) * 32 + i) * 32 + 8 * ch)); }
;         if (tid >= 128 && tid < 192) R.rd = DC[((size_t)seq * 72 + c) * 64 + (tid - 128)];
;     };
;     auto storel = [&](const GlaRegs& R, int buf) {
;         unsigned char* base = smem + buf * BUFB;
;         bf16_t* sat = (bf16_t*)base; bf16_t* sqt = (bf16_t*)(base + 2560); bf16_t* sko = (bf16_t*)(base + 2560 + 4608); bf16_t* sv = (bf16_t*)(base + 2560 + 9216); float* sdc = (float*)(base + 2560 + 9216 + 8704);
;         { const int pos = tid >> 4, ch = tid & 15; *(u32x4*)(sv + pos * 136 + 8 * ch) = R.rv; }
;         { const int t2 = tid & 255, pos = t2 >> 3, ch = t2 & 7; *(u32x4*)((tid < 256 ? sqt : sko) + pos * 72 + 8 * ch) = R.rq; }
;         if (tid < 128) { const int i = tid >> 2, ch = tid & 3; *(u32x4*)(sat + i * 40 + 8 * ch) = R.ra; }
;         if (tid >= 128 && tid < 192) sdc[tid - 128] = R.rd;
;     };
;     f32x4 st[4];
; #pragma unroll
;     for (int i = 0; i < 4; ++i) st[i] = (f32x4){0.f, 0.f, 0.f, 0.f};
;     const int sgn = dir ? -1 : 1;
;     auto compute = [&](int c) {
;         const unsigned char* base = smem + (c & 1) * BUFB;
;         const bf16_t* sat = (const bf16_t*)base; const bf16_t* sqt = (const bf16_t*)(base + 2560); const bf16_t* sko = (const bf16_t*)(base + 2560 + 4608); const bf16_t* sv = (const bf16_t*)(base + 2560 + 9216); const float* sdc = (const float*)(base + 2560 + 9216 + 8704);
;         const int dv0 = 16 * w;
;         const bf16x8 vb = tr2(sv + (8 * g + q4) * 136 + dv0 + 4 * p4, sv + (8 * g + 4 + q4) * 136 + dv0 + 4 * p4);
;         bf16x8 bs[2];
;         bs[0] = packacc(st[0], st[1]); bs[1] = packacc(st[2], st[3]);
; #pragma unroll
;         for (int mt = 0; mt < 2; ++mt) {
;             f32x4 acc = (f32x4){0.f, 0.f, 0.f, 0.f};
.LBB0_590:
	ds_read_b64_tr_b16 v[200:201], v123 offset:11776
	ds_read_b64_tr_b16 v[202:203], v124 offset:11776
	ds_read_b128 v[204:207], v125
	ds_read_b128 v[216:219], v127
	ds_read_b64_tr_b16 v[238:239], v144 offset:7168
	ds_read_b64_tr_b16 v[242:243], v144 offset:7200
	ds_read_b64_tr_b16 v[236:237], v143 offset:7168
	ds_read_b64_tr_b16 v[240:241], v143 offset:7200
	ds_read_b64_tr_b16 v[248:249], v143 offset:7232
	ds_read_b64_tr_b16 v[250:251], v144 offset:7232
	v_cvt_pk_bf16_f32 v96, v84, v85
	v_cvt_pk_bf16_f32 v99, v78, v79
	v_add_u32_e32 v152, 0x800, v126
	ds_read2_b64 v[208:211], v152 offset0:64 offset1:68
	ds_read2_b64 v[212:215], v152 offset0:72 offset1:76
	v_cvt_pk_bf16_f32 v98, v76, v77
	v_cvt_pk_bf16_f32 v97, v86, v87
	s_sub_i32 s4, s26, 64
	s_add_i32 s5, s26, 0xfffffec0
	s_add_i32 s6, s27, 0xa0
	s_add_i32 s7, s27, 0xfffff8a0
	s_waitcnt lgkmcnt(9)
	v_mfma_f32_16x16x32_bf16 v[92:95], v[200:203], v[204:207], 0
	s_and_b64 s[2:3], s[0:1], exec
	s_cselect_b32 s2, s4, s7
	s_add_i32 s4, s2, s22
	s_and_b64 s[2:3], s[0:1], exec
	s_waitcnt lgkmcnt(1)
	v_mfma_f32_16x16x32_bf16 v[92:95], v[96:99], v[208:211], v[92:95]
	ds_read_b64_tr_b16 v[208:209], v143 offset:7264
	ds_read_b64_tr_b16 v[210:211], v144 offset:7264
	v_cvt_pk_bf16_f32 v156, v72, v73
	v_cvt_pk_bf16_f32 v155, v82, v83
	v_cvt_pk_bf16_f32 v154, v80, v81
	v_cvt_pk_bf16_f32 v157, v74, v75
	s_cselect_b32 s2, s5, s6
	s_add_i32 s5, s2, s21
	s_cmp_lt_u32 s24, 8
	s_cselect_b64 s[36:37], -1, 0
	s_waitcnt lgkmcnt(2)
	v_mfma_f32_16x16x32_bf16 v[92:95], v[154:157], v[212:215], v[92:95]
	s_and_b64 s[2:3], s[36:37], exec
	s_cselect_b32 s2, s4, s5
	s_ashr_i32 s3, s2, 31
	s_lshl_b64 s[42:43], s[2:3], 10
	v_add_u32_e32 v151, 0x800, v142
	ds_read2_b64 v[224:227], v151 offset0:64 offset1:68
	ds_read2_b64 v[228:231], v151 offset0:72 offset1:76
	s_nop 2
	v_cvt_pk_bf16_f32 v92, v92, v93
	v_cvt_pk_bf16_f32 v93, v94, v95
	v_lshl_add_u64 v[94:95], v[100:101], 0, s[42:43]
	global_store_dwordx2 v[94:95], v[92:93], off
	v_mfma_f32_16x16x32_bf16 v[92:95], v[200:203], v[216:219], 0
	v_add_u32_e32 v153, 0x5000, v145
	ds_read2_b32 v[232:233], v153 offset1:1
	s_waitcnt lgkmcnt(2)
	v_mfma_f32_16x16x32_bf16 v[92:95], v[96:99], v[224:227], v[92:95]
	v_add_u32_e32 v158, 0x5040, v145
	ds_read2_b32 v[244:245], v158 offset1:1
	v_add_u32_e32 v161, 0x50c0, v145
	ds_read2_b32 v[212:213], v161 offset1:1
	s_waitcnt lgkmcnt(3)
	v_mfma_f32_16x16x32_bf16 v[92:95], v[154:157], v[228:231], v[92:95]
	v_add_u32_e32 v156, 0x5008, v145
	ds_read2_b32 v[234:235], v156 offset1:1
	v_add_u32_e32 v157, 0x5048, v145
	ds_read2_b32 v[246:247], v157 offset1:1
	v_add_u32_e32 v154, 0x5080, v145
	ds_read2_b32 v[204:205], v154 offset1:1
	s_nop 4
	v_cvt_pk_bf16_f32 v92, v92, v93
	v_cvt_pk_bf16_f32 v93, v94, v95
	v_lshl_add_u64 v[94:95], v[102:103], 0, s[42:43]
	global_store_dwordx2 v[94:95], v[92:93], off
	v_add_u32_e32 v155, 0x5088, v145
	ds_read2_b32 v[206:207], v155 offset1:1
	v_add_u32_e32 v160, 0x50c8, v145
	ds_read2_b32 v[214:215], v160 offset1:1
	s_waitcnt lgkmcnt(7)
	v_pk_mul_f32 v[84:85], v[84:85], v[232:233]
	s_waitcnt lgkmcnt(4)
	v_pk_mul_f32 v[86:87], v[86:87], v[234:235]
	s_nop 1
	v_mfma_f32_16x16x32_bf16 v[84:87], v[236:239], v[200:203], v[84:87]
	v_pk_mul_f32 v[76:77], v[76:77], v[244:245]
	s_waitcnt lgkmcnt(3)
	v_pk_mul_f32 v[78:79], v[78:79], v[246:247]
	s_nop 1
	v_mfma_f32_16x16x32_bf16 v[76:79], v[240:243], v[200:203], v[76:79]
	s_waitcnt lgkmcnt(2)
	v_pk_mul_f32 v[80:81], v[80:81], v[204:205]
	s_waitcnt lgkmcnt(1)
	v_pk_mul_f32 v[82:83], v[82:83], v[206:207]
	s_nop 1
	v_mfma_f32_16x16x32_bf16 v[80:83], v[248:251], v[200:203], v[80:83]
	s_waitcnt vmcnt(11)
	ds_write_b128 v121, v[12:15] offset:32512
	s_waitcnt vmcnt(10)
	ds_write_b128 v122, v[20:23] offset:20736
	v_pk_mul_f32 v[72:73], v[72:73], v[212:213]
	s_waitcnt lgkmcnt(2)
	v_pk_mul_f32 v[74:75], v[74:75], v[214:215]
	s_nop 1
	v_mfma_f32_16x16x32_bf16 v[72:75], v[208:211], v[200:203], v[72:75]
	s_waitcnt lgkmcnt(0)
	s_and_saveexec_b64 s[42:43], s[38:39]
	ds_write_b128 v148, v[16:19] offset:20736
	s_or_b64 exec, exec, s[42:43]
	s_and_saveexec_b64 s[42:43], s[40:41]
	ds_write_b32 v149, v116 offset:40704
	s_or_b64 exec, exec, s[42:43]
	s_cmp_gt_u32 s24, 64
	s_waitcnt lgkmcnt(0)
	s_barrier
	s_cbranch_scc1 .LBB0_600
	v_add_u32_e32 v12, 0xa0, v150
	s_movk_i32 s2, 0x100
	v_cmp_gt_i32_e32 vcc, s2, v12
	v_add_u32_e32 v13, 0xffffffa0, v150
	v_mov_b32_e32 v15, s22
	v_cndmask_b32_e32 v14, v174, v175, vcc
	v_add3_u32 v14, v132, v14, s27
	v_cndmask_b32_e32 v12, v13, v12, vcc
	v_mov_b32_e32 v13, s21
	v_add_u32_e32 v14, 0xfffff6c1, v14
	v_cndmask_b32_e32 v13, v13, v15, vcc
	v_cndmask_b32_e64 v12, v14, v12, s[0:1]
	v_add_u32_e32 v12, v12, v13
	s_movk_i32 s2, 0x3800
	v_add_co_u32_e32 v20, vcc, 0x7000, v112
	v_mad_i64_i32 v[12:13], s[2:3], v12, s2, v[104:105]
	s_nop 0
	v_addc_co_u32_e32 v21, vcc, 0, v113, vcc
	global_load_dwordx4 v[12:15], v[12:13], off offset:1024
	s_nop 0
	global_load_dwordx4 v[20:23], v[20:21], off nt
	s_and_saveexec_b64 s[42:43], s[38:39]
	s_cbranch_execz .LBB0_597
	v_lshl_add_u64 v[16:17], v[106:107], 0, s[44:45]
	v_add_co_u32_e32 v16, vcc, 0x1283f000, v16
	s_nop 1
	v_addc_co_u32_e32 v17, vcc, 0, v17, vcc
	global_load_dwordx4 v[16:19], v[16:17], off offset:2048 nt

; DI void gla_scan_item(const P& p, int seq, unsigned char* smem) {
;     ...
;     auto loadr = [&](GlaRegs& R, int c) {
;         if (c >= 72) return;
;         { const int pos = tid >> 4, ch = tid & 15; R.rv = *(const u32x4*)(S + (size_t)prow(b, dir, 32 * c + pos) * NP + C_GLA_V + 128 * h + 8 * ch); }
;         { const int t2 = tid & 255, pos = t2 >> 3, ch = t2 & 7; const bf16_t* src = (tid < 256 ? QT : KO) + ((size_t)seq * PT + 32 * c + pos) * 64 + 8 * ch; R.rq = __builtin_nontemporal_load((const u32x4*)src); }
;         if (tid < 128) { const int i = tid >> 2, ch = tid & 3; R.ra = __builtin_nontemporal_load((const u32x4*)(AT + (((size_t)seq * 72 + c) * 32 + i) * 32 + 8 * ch)); }
;         if (tid >= 128 && tid < 192) R.rd = DC[((size_t)seq * 72 + c) * 64 + (tid - 128)];
;     };
;     auto storel = [&](const GlaRegs& R, int buf) {
;         unsigned char* base = smem + buf * BUFB;
;         bf16_t* sat = (bf16_t*)base; bf16_t* sqt = (bf16_t*)(base + 2560); bf16_t* sko = (bf16_t*)(base + 2560 + 4608); bf16_t* sv = (bf16_t*)(base + 2560 + 9216); float* sdc = (float*)(base + 2560 + 9216 + 8704);
;         { const int pos = tid >> 4, ch = tid & 15; *(u32x4*)(sv + pos * 136 + 8 * ch) = R.rv; }
;         { const int t2 = tid & 255, pos = t2 >> 3, ch = t2 & 7; *(u32x4*)((tid < 256 ? sqt : sko) + pos * 72 + 8 * ch) = R.rq; }
;         if (tid < 128) { const int i = tid >> 2, ch = tid & 3; *(u32x4*)(sat + i * 40 + 8 * ch) = R.ra; }
;         if (tid >= 128 && tid < 192) sdc[tid - 128] = R.rd;
;     };
;     f32x4 st[4];
; #pragma unroll
;     for (int i = 0; i < 4; ++i) st[i] = (f32x4){0.f, 0.f, 0.f, 0.f};
;     const int sgn = dir ? -1 : 1;
;     auto compute = [&](int c) {
;         const unsigned char* base = smem + (c & 1) * BUFB;
;         const bf16_t* sat = (const bf16_t*)base; const bf16_t* sqt = (const bf16_t*)(base + 2560); const bf16_t* sko = (const bf16_t*)(base + 2560 + 4608); const bf16_t* sv = (const bf16_t*)(base + 2560 + 9216); const float* sdc = (const float*)(base + 2560 + 9216 + 8704);
;         const int dv0 = 16 * w;
;         const bf16x8 vb = tr2(sv + (8 * g + q4) * 136 + dv0 + 4 * p4, sv + (8 * g + 4 + q4) * 136 + dv0 + 4 * p4);
;         bf16x8 bs[2];
;         bs[0] = packacc(st[0], st[1]); bs[1] = packacc(st[2], st[3]);
; #pragma unroll
;         for (int mt = 0; mt < 2; ++mt) {
;             f32x4 acc = (f32x4){0.f, 0.f, 0.f, 0.f};
.LBB0_600:
	ds_read_b64_tr_b16 v[200:201], v123 offset:32512
	ds_read_b64_tr_b16 v[202:203], v124 offset:32512
	ds_read_b128 v[204:207], v125 offset:20736
	ds_read_b128 v[216:219], v127 offset:20736
	ds_read_b64_tr_b16 v[238:239], v147 offset:27904
	ds_read_b64_tr_b16 v[242:243], v147 offset:27936
	ds_read_b64_tr_b16 v[236:237], v146 offset:27904
	ds_read_b64_tr_b16 v[240:241], v146 offset:27936
	ds_read_b64_tr_b16 v[248:249], v146 offset:27968
	ds_read_b64_tr_b16 v[250:251], v147 offset:27968
	v_cvt_pk_bf16_f32 v96, v84, v85
	v_cvt_pk_bf16_f32 v99, v78, v79
	v_add_u32_e32 v159, 0x5800, v126
	ds_read2_b64 v[208:211], v159 offset0:96 offset1:100
	ds_read2_b64 v[212:215], v159 offset0:104 offset1:108
	v_cvt_pk_bf16_f32 v98, v76, v77
	v_cvt_pk_bf16_f32 v97, v86, v87
	s_waitcnt lgkmcnt(9)
	v_mfma_f32_16x16x32_bf16 v[88:91], v[200:203], v[204:207], 0
	s_sub_i32 s4, s26, 32
	s_add_i32 s5, s26, 0xfffffee0
	s_add_i32 s6, s27, 0x80
	s_add_i32 s7, s27, 0xfffff880
	s_and_b64 s[2:3], s[0:1], exec
	s_waitcnt lgkmcnt(1)
	v_mfma_f32_16x16x32_bf16 v[162:165], v[96:99], v[208:211], v[88:91]
	ds_read_b64_tr_b16 v[208:209], v146 offset:28000
	ds_read_b64_tr_b16 v[210:211], v147 offset:28000
	s_cselect_b32 s2, s4, s7
	s_add_i32 s4, s2, s22
	s_and_b64 s[2:3], s[0:1], exec
	v_cvt_pk_bf16_f32 v90, v72, v73
	v_cvt_pk_bf16_f32 v89, v82, v83
	v_cvt_pk_bf16_f32 v88, v80, v81
	v_cvt_pk_bf16_f32 v91, v74, v75
	s_cselect_b32 s2, s5, s6
	s_add_i32 s5, s2, s21
	s_waitcnt lgkmcnt(2)
	v_mfma_f32_16x16x32_bf16 v[162:165], v[88:91], v[212:215], v[162:165]
	s_and_b64 s[2:3], s[36:37], exec
	s_cselect_b32 s2, s4, s5
	s_ashr_i32 s3, s2, 31
	s_lshl_b64 s[36:37], s[2:3], 10
	s_nop 3
	v_cvt_pk_bf16_f32 v134, v162, v163
	v_cvt_pk_bf16_f32 v135, v164, v165
	v_lshl_add_u64 v[162:163], v[100:101], 0, s[36:37]
	global_store_dwordx2 v[162:163], v[134:135], off
	v_mfma_f32_16x16x32_bf16 v[184:187], v[200:203], v[216:219], 0
	v_add_u32_e32 v162, 0x5800, v142
	ds_read2_b64 v[224:227], v162 offset0:96 offset1:100
	ds_read2_b64 v[228:231], v162 offset0:104 offset1:108
	v_add_u32_e32 v163, 0xa100, v145
	ds_read2_b32 v[232:233], v163 offset1:1
	s_waitcnt lgkmcnt(2)
	v_mfma_f32_16x16x32_bf16 v[96:99], v[96:99], v[224:227], v[184:187]
	s_nop 2
	v_add_u32_e32 v183, 0xa108, v145
	ds_read2_b32 v[234:235], v183 offset1:1
	v_add_u32_e32 v164, 0xa180, v145
	ds_read2_b32 v[204:205], v164 offset1:1
	s_waitcnt lgkmcnt(3)
	v_mfma_f32_16x16x32_bf16 v[88:91], v[88:91], v[228:231], v[96:99]
	v_add_u32_e32 v185, 0xa140, v145
	ds_read2_b32 v[244:245], v185 offset1:1
	v_add_u32_e32 v184, 0xa148, v145
	ds_read2_b32 v[246:247], v184 offset1:1
	v_add_u32_e32 v165, 0xa188, v145
	ds_read2_b32 v[206:207], v165 offset1:1
	s_nop 4
	v_cvt_pk_bf16_f32 v88, v88, v89
	v_cvt_pk_bf16_f32 v89, v90, v91
	v_lshl_add_u64 v[90:91], v[102:103], 0, s[36:37]
	global_store_dwordx2 v[90:91], v[88:89], off
	v_add_u32_e32 v187, 0xa1c0, v145
	ds_read2_b32 v[212:213], v187 offset1:1
	v_add_u32_e32 v186, 0xa1c8, v145
	ds_read2_b32 v[214:215], v186 offset1:1
	s_waitcnt lgkmcnt(7)
	v_pk_mul_f32 v[84:85], v[84:85], v[232:233]
	s_waitcnt lgkmcnt(6)
	v_pk_mul_f32 v[86:87], v[86:87], v[234:235]
	s_nop 1
	v_mfma_f32_16x16x32_bf16 v[88:91], v[236:239], v[200:203], v[84:87]
	s_nop 2
	s_waitcnt lgkmcnt(4)
	v_pk_mul_f32 v[76:77], v[76:77], v[244:245]
	s_waitcnt lgkmcnt(3)
	v_pk_mul_f32 v[78:79], v[78:79], v[246:247]
	s_nop 1
	v_mfma_f32_16x16x32_bf16 v[84:87], v[240:243], v[200:203], v[76:79]
	s_nop 2
	v_pk_mul_f32 v[80:81], v[80:81], v[204:205]
	s_waitcnt lgkmcnt(2)
	v_pk_mul_f32 v[82:83], v[82:83], v[206:207]
	s_nop 1
	v_mfma_f32_16x16x32_bf16 v[76:79], v[248:251], v[200:203], v[80:83]
	s_nop 2
	s_waitcnt vmcnt(11)
	ds_write_b128 v121, v[24:27] offset:11776
	s_waitcnt vmcnt(10)
	ds_write_b128 v122, v[32:35]
	s_waitcnt lgkmcnt(3)
	v_pk_mul_f32 v[72:73], v[72:73], v[212:213]
	s_waitcnt lgkmcnt(2)
	v_pk_mul_f32 v[74:75], v[74:75], v[214:215]
	s_nop 1
	v_mfma_f32_16x16x32_bf16 v[80:83], v[208:211], v[200:203], v[72:75]
	s_waitcnt lgkmcnt(0)
	s_and_saveexec_b64 s[36:37], s[38:39]
	ds_write_b128 v148, v[28:31]
	s_or_b64 exec, exec, s[36:37]
	s_and_saveexec_b64 s[36:37], s[40:41]
	ds_write_b32 v149, v117 offset:19968
	s_or_b64 exec, exec, s[36:37]
	s_cmp_gt_u32 s24, 63
	s_waitcnt lgkmcnt(0)
	s_barrier
	s_cbranch_scc1 .LBB0_610
	v_add_u32_e32 v24, 0xc0, v150
	s_movk_i32 s2, 0x100
	v_cmp_gt_i32_e32 vcc, s2, v24
	v_subrev_u32_e32 v25, 64, v150
	v_mov_b32_e32 v27, s22
	v_cndmask_b32_e32 v26, v174, v175, vcc
	v_add3_u32 v26, v132, v26, s27
	v_cndmask_b32_e32 v24, v25, v24, vcc
	v_mov_b32_e32 v25, s21
	v_add_u32_e32 v26, 0xfffff6a1, v26
	v_cndmask_b32_e32 v25, v25, v27, vcc
	v_cndmask_b32_e64 v24, v26, v24, s[0:1]
	v_add_u32_e32 v24, v24, v25
	s_movk_i32 s2, 0x3800
	v_add_co_u32_e32 v32, vcc, 0x8000, v112
	v_mad_i64_i32 v[24:25], s[2:3], v24, s2, v[104:105]
	s_nop 0
	v_addc_co_u32_e32 v33, vcc, 0, v113, vcc
	global_load_dwordx4 v[24:27], v[24:25], off offset:1024
	s_nop 0
	global_load_dwordx4 v[32:35], v[32:33], off nt
	s_and_saveexec_b64 s[36:37], s[38:39]
	s_cbranch_execz .LBB0_607
	v_lshl_add_u64 v[28:29], v[106:107], 0, s[44:45]
	v_add_co_u32_e32 v28, vcc, 0x12840000, v28
	s_nop 1
	v_addc_co_u32_e32 v29, vcc, 0, v29, vcc
	global_load_dwordx4 v[28:31], v[28:29], off nt

; DI void gla_scan_item(const P& p, int seq, unsigned char* smem) {
;     ...
;     auto loadr = [&](GlaRegs& R, int c) {
;         if (c >= 72) return;
;         { const int pos = tid >> 4, ch = tid & 15; R.rv = *(const u32x4*)(S + (size_t)prow(b, dir, 32 * c + pos) * NP + C_GLA_V + 128 * h + 8 * ch); }
;         { const int t2 = tid & 255, pos = t2 >> 3, ch = t2 & 7; const bf16_t* src = (tid < 256 ? QT : KO) + ((size_t)seq * PT + 32 * c + pos) * 64 + 8 * ch; R.rq = __builtin_nontemporal_load((const u32x4*)src); }
;         if (tid < 128) { const int i = tid >> 2, ch = tid & 3; R.ra = __builtin_nontemporal_load((const u32x4*)(AT + (((size_t)seq * 72 + c) * 32 + i) * 32 + 8 * ch)); }
;         if (tid >= 128 && tid < 192) R.rd = DC[((size_t)seq * 72 + c) * 64 + (tid - 128)];
;     };
;     auto storel = [&](const GlaRegs& R, int buf) {
;         unsigned char* base = smem + buf * BUFB;
;         bf16_t* sat = (bf16_t*)base; bf16_t* sqt = (bf16_t*)(base + 2560); bf16_t* sko = (bf16_t*)(base + 2560 + 4608); bf16_t* sv = (bf16_t*)(base + 2560 + 9216); float* sdc = (float*)(base + 2560 + 9216 + 8704);
;         { const int pos = tid >> 4, ch = tid & 15; *(u32x4*)(sv + pos * 136 + 8 * ch) = R.rv; }
;         { const int t2 = tid & 255, pos = t2 >> 3, ch = t2 & 7; *(u32x4*)((tid < 256 ? sqt : sko) + pos * 72 + 8 * ch) = R.rq; }
;         if (tid < 128) { const int i = tid >> 2, ch = tid & 3; *(u32x4*)(sat + i * 40 + 8 * ch) = R.ra; }
;         if (tid >= 128 && tid < 192) sdc[tid - 128] = R.rd;
;     };
;     f32x4 st[4];
; #pragma unroll
;     for (int i = 0; i < 4; ++i) st[i] = (f32x4){0.f, 0.f, 0.f, 0.f};
;     const int sgn = dir ? -1 : 1;
;     auto compute = [&](int c) {
;         const unsigned char* base = smem + (c & 1) * BUFB;
;         const bf16_t* sat = (const bf16_t*)base; const bf16_t* sqt = (const bf16_t*)(base + 2560); const bf16_t* sko = (const bf16_t*)(base + 2560 + 4608); const bf16_t* sv = (const bf16_t*)(base + 2560 + 9216); const float* sdc = (const float*)(base + 2560 + 9216 + 8704);
;         const int dv0 = 16 * w;
;         const bf16x8 vb = tr2(sv + (8 * g + q4) * 136 + dv0 + 4 * p4, sv + (8 * g + 4 + q4) * 136 + dv0 + 4 * p4);
;         bf16x8 bs[2];
;         bs[0] = packacc(st[0], st[1]); bs[1] = packacc(st[2], st[3]);
; #pragma unroll
;         for (int mt = 0; mt < 2; ++mt) {
;             f32x4 acc = (f32x4){0.f, 0.f, 0.f, 0.f};
.LBB0_610:
	ds_read_b64_tr_b16 v[200:201], v123 offset:11776
	ds_read_b64_tr_b16 v[202:203], v124 offset:11776
	ds_read_b128 v[204:207], v125
	ds_read2_b64 v[208:211], v152 offset0:64 offset1:68
	ds_read2_b64 v[212:215], v152 offset0:72 offset1:76
	ds_read2_b64 v[216:219], v151 offset0:64 offset1:68
	ds_read_b128 v[224:227], v127
	ds_read2_b64 v[228:231], v151 offset0:72 offset1:76
	ds_read2_b32 v[232:233], v153 offset1:1
	ds_read2_b32 v[234:235], v156 offset1:1
	ds_read_b64_tr_b16 v[238:239], v144 offset:7168
	ds_read_b64_tr_b16 v[242:243], v144 offset:7200
	v_cvt_pk_bf16_f32 v98, v84, v85
	v_cvt_pk_bf16_f32 v97, v90, v91
	v_cvt_pk_bf16_f32 v96, v88, v89
	v_cvt_pk_bf16_f32 v99, v86, v87
	s_waitcnt lgkmcnt(9)
	v_mfma_f32_16x16x32_bf16 v[72:75], v[200:203], v[204:207], 0
	ds_read_b64_tr_b16 v[236:237], v143 offset:7168
	ds_read_b64_tr_b16 v[240:241], v143 offset:7200
	ds_read2_b32 v[244:245], v158 offset1:1
	s_add_i32 s4, s26, 0xffffff00
	s_add_i32 s5, s27, 0x60
	s_add_i32 s6, s27, 0xfffff860
	s_and_b64 s[2:3], s[0:1], exec
	s_cselect_b32 s2, s26, s6
	s_waitcnt lgkmcnt(11)
	v_mfma_f32_16x16x32_bf16 v[72:75], v[96:99], v[208:211], v[72:75]
	ds_read2_b32 v[246:247], v157 offset1:1
	v_cvt_pk_bf16_f32 v190, v80, v81
	v_cvt_pk_bf16_f32 v189, v78, v79
	v_cvt_pk_bf16_f32 v188, v76, v77
	v_cvt_pk_bf16_f32 v191, v82, v83
	s_add_i32 s6, s2, s22
	s_and_b64 s[2:3], s[0:1], exec
	s_cselect_b32 s2, s4, s5
	s_add_i32 s2, s2, s21
	s_cmp_lt_u32 s24, 6
	s_waitcnt lgkmcnt(11)
	v_mfma_f32_16x16x32_bf16 v[72:75], v[188:191], v[212:215], v[72:75]
	ds_read_b64_tr_b16 v[248:249], v143 offset:7232
	s_cselect_b32 s2, s6, s2
	s_ashr_i32 s3, s2, 31
	s_lshl_b64 s[36:37], s[2:3], 10
	s_nop 3
	v_cvt_pk_bf16_f32 v72, v72, v73
	v_cvt_pk_bf16_f32 v73, v74, v75
	v_lshl_add_u64 v[74:75], v[100:101], 0, s[36:37]
	global_store_dwordx2 v[74:75], v[72:73], off
	s_waitcnt lgkmcnt(10)
	v_mfma_f32_16x16x32_bf16 v[72:75], v[200:203], v[224:227], 0
	ds_read_b64_tr_b16 v[250:251], v144 offset:7232
	ds_read2_b32 v[204:205], v154 offset1:1
	v_mfma_f32_16x16x32_bf16 v[72:75], v[96:99], v[216:219], v[72:75]
	s_waitcnt lgkmcnt(11)
	v_mfma_f32_16x16x32_bf16 v[72:75], v[188:191], v[228:231], v[72:75]
	ds_read2_b32 v[206:207], v155 offset1:1
	s_nop 7
	v_cvt_pk_bf16_f32 v72, v72, v73
	v_cvt_pk_bf16_f32 v73, v74, v75
	v_lshl_add_u64 v[74:75], v[102:103], 0, s[36:37]
	global_store_dwordx2 v[74:75], v[72:73], off
	s_waitcnt lgkmcnt(11)
	v_pk_mul_f32 v[72:73], v[88:89], v[232:233]
	ds_read_b64_tr_b16 v[208:209], v143 offset:7264
	s_waitcnt lgkmcnt(11)
	v_pk_mul_f32 v[74:75], v[90:91], v[234:235]
	ds_read_b64_tr_b16 v[210:211], v144 offset:7264
	s_waitcnt lgkmcnt(9)
	v_mfma_f32_16x16x32_bf16 v[88:91], v[236:239], v[200:203], v[72:75]
	ds_read2_b32 v[212:213], v161 offset1:1
	ds_read2_b32 v[214:215], v160 offset1:1
	s_nop 2
	s_waitcnt lgkmcnt(9)
	v_pk_mul_f32 v[72:73], v[84:85], v[244:245]
	s_waitcnt lgkmcnt(8)
	v_pk_mul_f32 v[74:75], v[86:87], v[246:247]
	s_nop 1
	v_mfma_f32_16x16x32_bf16 v[72:75], v[240:243], v[200:203], v[72:75]
	s_waitcnt lgkmcnt(5)
	v_pk_mul_f32 v[76:77], v[76:77], v[204:205]
	s_waitcnt lgkmcnt(4)
	v_pk_mul_f32 v[78:79], v[78:79], v[206:207]
	s_nop 1
	v_mfma_f32_16x16x32_bf16 v[76:79], v[248:251], v[200:203], v[76:79]
	s_waitcnt vmcnt(11)
	ds_write_b128 v121, v[36:39] offset:32512
	s_waitcnt vmcnt(10)
	ds_write_b128 v122, v[44:47] offset:20736
	s_waitcnt lgkmcnt(3)
	v_pk_mul_f32 v[80:81], v[80:81], v[212:213]
	s_waitcnt lgkmcnt(2)
	v_pk_mul_f32 v[82:83], v[82:83], v[214:215]
	s_nop 1
	v_mfma_f32_16x16x32_bf16 v[80:83], v[208:211], v[200:203], v[80:83]
	s_waitcnt lgkmcnt(0)
	s_and_saveexec_b64 s[36:37], s[38:39]
	ds_write_b128 v148, v[40:43] offset:20736
	s_or_b64 exec, exec, s[36:37]
	s_and_saveexec_b64 s[36:37], s[40:41]
	ds_write_b32 v149, v118 offset:40704
	s_or_b64 exec, exec, s[36:37]
	s_cmp_gt_u32 s24, 62
	s_waitcnt lgkmcnt(0)
	s_barrier
	s_cbranch_scc1 .LBB0_620
	v_add_u32_e32 v36, 0xe0, v150
	s_movk_i32 s2, 0x100
	v_cmp_gt_i32_e32 vcc, s2, v36
	v_subrev_u32_e32 v37, 32, v150
	v_mov_b32_e32 v39, s22
	v_cndmask_b32_e32 v38, v174, v175, vcc
	v_add3_u32 v38, v132, v38, s27
	v_cndmask_b32_e32 v36, v37, v36, vcc
	v_mov_b32_e32 v37, s21
	v_add_u32_e32 v38, 0xfffff681, v38
	v_cndmask_b32_e32 v37, v37, v39, vcc
	v_cndmask_b32_e64 v36, v38, v36, s[0:1]
	v_add_u32_e32 v36, v36, v37
	s_movk_i32 s2, 0x3800
	v_add_co_u32_e32 v44, vcc, 0x9000, v112
	v_mad_i64_i32 v[36:37], s[2:3], v36, s2, v[104:105]
	s_nop 0
	v_addc_co_u32_e32 v45, vcc, 0, v113, vcc
	global_load_dwordx4 v[36:39], v[36:37], off offset:1024
	s_nop 0
	global_load_dwordx4 v[44:47], v[44:45], off nt
	s_and_saveexec_b64 s[36:37], s[38:39]
	s_cbranch_execz .LBB0_617
	v_lshl_add_u64 v[40:41], v[106:107], 0, s[44:45]
	v_add_co_u32_e32 v40, vcc, 0x12840000, v40
	s_nop 1
	v_addc_co_u32_e32 v41, vcc, 0, v41, vcc
	global_load_dwordx4 v[40:43], v[40:41], off offset:2048 nt

; DI void gla_scan_item(const P& p, int seq, unsigned char* smem) {
;     ...
;     auto loadr = [&](GlaRegs& R, int c) {
;         if (c >= 72) return;
;         { const int pos = tid >> 4, ch = tid & 15; R.rv = *(const u32x4*)(S + (size_t)prow(b, dir, 32 * c + pos) * NP + C_GLA_V + 128 * h + 8 * ch); }
;         { const int t2 = tid & 255, pos = t2 >> 3, ch = t2 & 7; const bf16_t* src = (tid < 256 ? QT : KO) + ((size_t)seq * PT + 32 * c + pos) * 64 + 8 * ch; R.rq = __builtin_nontemporal_load((const u32x4*)src); }
;         if (tid < 128) { const int i = tid >> 2, ch = tid & 3; R.ra = __builtin_nontemporal_load((const u32x4*)(AT + (((size_t)seq * 72 + c) * 32 + i) * 32 + 8 * ch)); }
;         if (tid >= 128 && tid < 192) R.rd = DC[((size_t)seq * 72 + c) * 64 + (tid - 128)];
;     };
;     auto storel = [&](const GlaRegs& R, int buf) {
;         unsigned char* base = smem + buf * BUFB;
;         bf16_t* sat = (bf16_t*)base; bf16_t* sqt = (bf16_t*)(base + 2560); bf16_t* sko = (bf16_t*)(base + 2560 + 4608); bf16_t* sv = (bf16_t*)(base + 2560 + 9216); float* sdc = (float*)(base + 2560 + 9216 + 8704);
;         { const int pos = tid >> 4, ch = tid & 15; *(u32x4*)(sv + pos * 136 + 8 * ch) = R.rv; }
;         { const int t2 = tid & 255, pos = t2 >> 3, ch = t2 & 7; *(u32x4*)((tid < 256 ? sqt : sko) + pos * 72 + 8 * ch) = R.rq; }
;         if (tid < 128) { const int i = tid >> 2, ch = tid & 3; *(u32x4*)(sat + i * 40 + 8 * ch) = R.ra; }
;         if (tid >= 128 && tid < 192) sdc[tid - 128] = R.rd;
;     };
;     f32x4 st[4];
; #pragma unroll
;     for (int i = 0; i < 4; ++i) st[i] = (f32x4){0.f, 0.f, 0.f, 0.f};
;     const int sgn = dir ? -1 : 1;
;     auto compute = [&](int c) {
;         const unsigned char* base = smem + (c & 1) * BUFB;
;         const bf16_t* sat = (const bf16_t*)base; const bf16_t* sqt = (const bf16_t*)(base + 2560); const bf16_t* sko = (const bf16_t*)(base + 2560 + 4608); const bf16_t* sv = (const bf16_t*)(base + 2560 + 9216); const float* sdc = (const float*)(base + 2560 + 9216 + 8704);
;         const int dv0 = 16 * w;
;         const bf16x8 vb = tr2(sv + (8 * g + q4) * 136 + dv0 + 4 * p4, sv + (8 * g + 4 + q4) * 136 + dv0 + 4 * p4);
;         bf16x8 bs[2];
;         bs[0] = packacc(st[0], st[1]); bs[1] = packacc(st[2], st[3]);
; #pragma unroll
;         for (int mt = 0; mt < 2; ++mt) {
;             f32x4 acc = (f32x4){0.f, 0.f, 0.f, 0.f};
.LBB0_620:
	ds_read_b64_tr_b16 v[200:201], v123 offset:32512
	ds_read_b64_tr_b16 v[202:203], v124 offset:32512
	ds_read_b128 v[204:207], v125 offset:20736
	ds_read2_b64 v[208:211], v159 offset0:96 offset1:100
	ds_read2_b64 v[212:215], v159 offset0:104 offset1:108
	ds_read2_b64 v[216:219], v162 offset0:96 offset1:100
	ds_read_b128 v[224:227], v127 offset:20736
	ds_read2_b64 v[228:231], v162 offset0:104 offset1:108
	ds_read2_b32 v[232:233], v163 offset1:1
	ds_read2_b32 v[234:235], v183 offset1:1
	ds_read_b64_tr_b16 v[238:239], v147 offset:27904
	ds_read_b64_tr_b16 v[242:243], v147 offset:27936
	v_cvt_pk_bf16_f32 v98, v72, v73
	v_cvt_pk_bf16_f32 v97, v90, v91
	v_cvt_pk_bf16_f32 v96, v88, v89
	v_cvt_pk_bf16_f32 v99, v74, v75
	s_waitcnt lgkmcnt(9)
	v_mfma_f32_16x16x32_bf16 v[92:95], v[200:203], v[204:207], 0
	ds_read_b64_tr_b16 v[236:237], v146 offset:27904
	ds_read_b64_tr_b16 v[240:241], v146 offset:27936
	ds_read2_b32 v[244:245], v185 offset1:1
	s_add_i32 s4, s26, 32
	s_add_i32 s5, s26, 0xffffff20
	s_add_i32 s6, s27, 64
	s_add_i32 s7, s27, 0xfffff840
	s_and_b64 s[2:3], s[0:1], exec
	s_cselect_b32 s2, s4, s7
	s_waitcnt lgkmcnt(11)
	v_mfma_f32_16x16x32_bf16 v[92:95], v[96:99], v[208:211], v[92:95]
	ds_read2_b32 v[246:247], v184 offset1:1
	v_cvt_pk_bf16_f32 v190, v80, v81
	v_cvt_pk_bf16_f32 v189, v78, v79
	v_cvt_pk_bf16_f32 v188, v76, v77
	v_cvt_pk_bf16_f32 v191, v82, v83
	s_add_i32 s4, s2, s22
	s_and_b64 s[2:3], s[0:1], exec
	s_cselect_b32 s2, s5, s6
	s_add_i32 s2, s2, s21
	s_cmp_lt_u32 s24, 5
	s_waitcnt lgkmcnt(11)
	v_mfma_f32_16x16x32_bf16 v[92:95], v[188:191], v[212:215], v[92:95]
	ds_read_b64_tr_b16 v[248:249], v146 offset:27968
	s_cselect_b32 s2, s4, s2
	s_ashr_i32 s3, s2, 31
	s_lshl_b64 s[36:37], s[2:3], 10
	s_nop 3
	v_cvt_pk_bf16_f32 v92, v92, v93
	v_cvt_pk_bf16_f32 v93, v94, v95
	v_lshl_add_u64 v[94:95], v[100:101], 0, s[36:37]
	global_store_dwordx2 v[94:95], v[92:93], off
	s_waitcnt lgkmcnt(10)
	v_mfma_f32_16x16x32_bf16 v[92:95], v[200:203], v[224:227], 0
	ds_read_b64_tr_b16 v[250:251], v147 offset:27968
	ds_read2_b32 v[204:205], v164 offset1:1
	v_mfma_f32_16x16x32_bf16 v[92:95], v[96:99], v[216:219], v[92:95]
	s_waitcnt lgkmcnt(11)
	v_mfma_f32_16x16x32_bf16 v[92:95], v[188:191], v[228:231], v[92:95]
	ds_read2_b32 v[206:207], v165 offset1:1
	s_nop 7
	v_cvt_pk_bf16_f32 v92, v92, v93
	v_cvt_pk_bf16_f32 v93, v94, v95
	v_lshl_add_u64 v[94:95], v[102:103], 0, s[36:37]
	global_store_dwordx2 v[94:95], v[92:93], off
	s_waitcnt lgkmcnt(11)
	v_pk_mul_f32 v[88:89], v[88:89], v[232:233]
	ds_read_b64_tr_b16 v[208:209], v146 offset:28000
	s_waitcnt lgkmcnt(11)
	v_pk_mul_f32 v[90:91], v[90:91], v[234:235]
	ds_read_b64_tr_b16 v[210:211], v147 offset:28000
	s_waitcnt lgkmcnt(9)
	v_mfma_f32_16x16x32_bf16 v[88:91], v[236:239], v[200:203], v[88:91]
	ds_read2_b32 v[212:213], v187 offset1:1
	ds_read2_b32 v[214:215], v186 offset1:1
	s_waitcnt lgkmcnt(9)
	v_pk_mul_f32 v[72:73], v[72:73], v[244:245]
	s_waitcnt lgkmcnt(8)
	v_pk_mul_f32 v[74:75], v[74:75], v[246:247]
	s_nop 1
	v_mfma_f32_16x16x32_bf16 v[72:75], v[240:243], v[200:203], v[72:75]
	s_waitcnt lgkmcnt(5)
	v_pk_mul_f32 v[76:77], v[76:77], v[204:205]
	s_waitcnt lgkmcnt(4)
	v_pk_mul_f32 v[78:79], v[78:79], v[206:207]
	s_nop 1
	v_mfma_f32_16x16x32_bf16 v[76:79], v[248:251], v[200:203], v[76:79]
	s_waitcnt vmcnt(11)
	ds_write_b128 v121, v[48:51] offset:11776
	s_waitcnt vmcnt(10)
	ds_write_b128 v122, v[56:59]
	s_waitcnt lgkmcnt(3)
	v_pk_mul_f32 v[80:81], v[80:81], v[212:213]
	s_waitcnt lgkmcnt(2)
	v_pk_mul_f32 v[82:83], v[82:83], v[214:215]
	s_nop 1
	v_mfma_f32_16x16x32_bf16 v[84:87], v[208:211], v[200:203], v[80:83]
	s_waitcnt lgkmcnt(0)
	s_and_saveexec_b64 s[36:37], s[38:39]
	ds_write_b128 v148, v[52:55]
	s_or_b64 exec, exec, s[36:37]
	s_and_saveexec_b64 s[36:37], s[40:41]
	ds_write_b32 v149, v119 offset:19968
	s_or_b64 exec, exec, s[36:37]
	s_cmp_gt_u32 s24, 61
	s_waitcnt lgkmcnt(0)
	s_barrier
	s_cbranch_scc1 .LBB0_630
	v_add_u32_e32 v48, 0x100, v150
	s_movk_i32 s2, 0x100
	v_cmp_gt_i32_e32 vcc, s2, v48
	v_mov_b32_e32 v50, s21
	v_mov_b32_e32 v51, s22
	v_cndmask_b32_e32 v49, v174, v175, vcc
	v_add3_u32 v49, v132, v49, s27
	v_cndmask_b32_e32 v48, v150, v48, vcc
	v_add_u32_e32 v49, 0xfffff661, v49
	v_cndmask_b32_e32 v50, v50, v51, vcc
	v_cndmask_b32_e64 v48, v49, v48, s[0:1]
	v_add_u32_e32 v48, v48, v50
	s_movk_i32 s2, 0x3800
	v_add_co_u32_e32 v56, vcc, 0xa000, v112
	v_mad_i64_i32 v[48:49], s[2:3], v48, s2, v[104:105]
	s_nop 0
	v_addc_co_u32_e32 v57, vcc, 0, v113, vcc
	global_load_dwordx4 v[48:51], v[48:49], off offset:1024
	s_nop 0
	global_load_dwordx4 v[56:59], v[56:57], off nt
	s_and_saveexec_b64 s[36:37], s[38:39]
	s_cbranch_execz .LBB0_627
	v_lshl_add_u64 v[52:53], v[106:107], 0, s[44:45]
	v_add_co_u32_e32 v52, vcc, 0x12841000, v52
	s_nop 1
	v_addc_co_u32_e32 v53, vcc, 0, v53, vcc
	global_load_dwordx4 v[52:55], v[52:53], off nt

; DI void gla_scan_item(const P& p, int seq, unsigned char* smem) {
;     ...
;     auto loadr = [&](GlaRegs& R, int c) {
;         if (c >= 72) return;
;         { const int pos = tid >> 4, ch = tid & 15; R.rv = *(const u32x4*)(S + (size_t)prow(b, dir, 32 * c + pos) * NP + C_GLA_V + 128 * h + 8 * ch); }
;         { const int t2 = tid & 255, pos = t2 >> 3, ch = t2 & 7; const bf16_t* src = (tid < 256 ? QT : KO) + ((size_t)seq * PT + 32 * c + pos) * 64 + 8 * ch; R.rq = __builtin_nontemporal_load((const u32x4*)src); }
;         if (tid < 128) { const int i = tid >> 2, ch = tid & 3; R.ra = __builtin_nontemporal_load((const u32x4*)(AT + (((size_t)seq * 72 + c) * 32 + i) * 32 + 8 * ch)); }
;         if (tid >= 128 && tid < 192) R.rd = DC[((size_t)seq * 72 + c) * 64 + (tid - 128)];
;     };
;     auto storel = [&](const GlaRegs& R, int buf) {
;         unsigned char* base = smem + buf * BUFB;
;         bf16_t* sat = (bf16_t*)base; bf16_t* sqt = (bf16_t*)(base + 2560); bf16_t* sko = (bf16_t*)(base + 2560 + 4608); bf16_t* sv = (bf16_t*)(base + 2560 + 9216); float* sdc = (float*)(base + 2560 + 9216 + 8704);
;         { const int pos = tid >> 4, ch = tid & 15; *(u32x4*)(sv + pos * 136 + 8 * ch) = R.rv; }
;         { const int t2 = tid & 255, pos = t2 >> 3, ch = t2 & 7; *(u32x4*)((tid < 256 ? sqt : sko) + pos * 72 + 8 * ch) = R.rq; }
;         if (tid < 128) { const int i = tid >> 2, ch = tid & 3; *(u32x4*)(sat + i * 40 + 8 * ch) = R.ra; }
;         if (tid >= 128 && tid < 192) sdc[tid - 128] = R.rd;
;     };
;     f32x4 st[4];
; #pragma unroll
;     for (int i = 0; i < 4; ++i) st[i] = (f32x4){0.f, 0.f, 0.f, 0.f};
;     const int sgn = dir ? -1 : 1;
;     auto compute = [&](int c) {
;         const unsigned char* base = smem + (c & 1) * BUFB;
;         const bf16_t* sat = (const bf16_t*)base; const bf16_t* sqt = (const bf16_t*)(base + 2560); const bf16_t* sko = (const bf16_t*)(base + 2560 + 4608); const bf16_t* sv = (const bf16_t*)(base + 2560 + 9216); const float* sdc = (const float*)(base + 2560 + 9216 + 8704);
;         const int dv0 = 16 * w;
;         const bf16x8 vb = tr2(sv + (8 * g + q4) * 136 + dv0 + 4 * p4, sv + (8 * g + 4 + q4) * 136 + dv0 + 4 * p4);
;         bf16x8 bs[2];
;         bs[0] = packacc(st[0], st[1]); bs[1] = packacc(st[2], st[3]);
; #pragma unroll
;         for (int mt = 0; mt < 2; ++mt) {
;             f32x4 acc = (f32x4){0.f, 0.f, 0.f, 0.f};
.LBB0_630:
	ds_read_b64_tr_b16 v[200:201], v123 offset:11776
	ds_read_b64_tr_b16 v[202:203], v124 offset:11776
	ds_read_b128 v[204:207], v125
	ds_read2_b64 v[208:211], v152 offset0:64 offset1:68
	ds_read2_b64 v[212:215], v152 offset0:72 offset1:76
	ds_read2_b64 v[216:219], v151 offset0:64 offset1:68
	ds_read_b128 v[224:227], v127
	ds_read2_b64 v[228:231], v151 offset0:72 offset1:76
	ds_read2_b32 v[232:233], v153 offset1:1
	ds_read2_b32 v[234:235], v156 offset1:1
	ds_read_b64_tr_b16 v[238:239], v144 offset:7168
	ds_read_b64_tr_b16 v[242:243], v144 offset:7200
	v_cvt_pk_bf16_f32 v94, v72, v73
	v_cvt_pk_bf16_f32 v93, v90, v91
	v_cvt_pk_bf16_f32 v92, v88, v89
	v_cvt_pk_bf16_f32 v95, v74, v75
	s_waitcnt lgkmcnt(9)
	v_mfma_f32_16x16x32_bf16 v[80:83], v[200:203], v[204:207], 0
	ds_read_b64_tr_b16 v[236:237], v143 offset:7168
	ds_read_b64_tr_b16 v[240:241], v143 offset:7200
	ds_read2_b32 v[244:245], v158 offset1:1
	s_add_i32 s4, s26, 64
	s_add_i32 s5, s26, 0xffffff40
	s_add_i32 s6, s27, 32
	s_add_i32 s7, s27, 0xfffff820
	s_and_b64 s[2:3], s[0:1], exec
	s_cselect_b32 s2, s4, s7
	s_waitcnt lgkmcnt(11)
	v_mfma_f32_16x16x32_bf16 v[80:83], v[92:95], v[208:211], v[80:83]
	ds_read2_b32 v[246:247], v157 offset1:1
	v_cvt_pk_bf16_f32 v190, v84, v85
	v_cvt_pk_bf16_f32 v189, v78, v79
	v_cvt_pk_bf16_f32 v188, v76, v77
	v_cvt_pk_bf16_f32 v191, v86, v87
	s_add_i32 s4, s2, s22
	s_and_b64 s[2:3], s[0:1], exec
	s_cselect_b32 s2, s5, s6
	s_add_i32 s2, s2, s21
	s_cmp_lt_u32 s24, 4
	s_waitcnt lgkmcnt(11)
	v_mfma_f32_16x16x32_bf16 v[80:83], v[188:191], v[212:215], v[80:83]
	ds_read_b64_tr_b16 v[248:249], v143 offset:7232
	s_cselect_b32 s2, s4, s2
	s_ashr_i32 s3, s2, 31
	s_lshl_b64 s[36:37], s[2:3], 10
	s_nop 3
	v_cvt_pk_bf16_f32 v80, v80, v81
	v_cvt_pk_bf16_f32 v81, v82, v83
	v_lshl_add_u64 v[82:83], v[100:101], 0, s[36:37]
	global_store_dwordx2 v[82:83], v[80:81], off
	s_waitcnt lgkmcnt(10)
	v_mfma_f32_16x16x32_bf16 v[80:83], v[200:203], v[224:227], 0
	ds_read_b64_tr_b16 v[250:251], v144 offset:7232
	ds_read2_b32 v[204:205], v154 offset1:1
	v_mfma_f32_16x16x32_bf16 v[80:83], v[92:95], v[216:219], v[80:83]
	s_waitcnt lgkmcnt(11)
	v_mfma_f32_16x16x32_bf16 v[80:83], v[188:191], v[228:231], v[80:83]
	ds_read2_b32 v[206:207], v155 offset1:1
	s_nop 7
	v_cvt_pk_bf16_f32 v80, v80, v81
	v_cvt_pk_bf16_f32 v81, v82, v83
	v_lshl_add_u64 v[82:83], v[102:103], 0, s[36:37]
	global_store_dwordx2 v[82:83], v[80:81], off
	s_waitcnt lgkmcnt(11)
	v_pk_mul_f32 v[80:81], v[88:89], v[232:233]
	ds_read_b64_tr_b16 v[208:209], v143 offset:7264
	s_waitcnt lgkmcnt(11)
	v_pk_mul_f32 v[82:83], v[90:91], v[234:235]
	ds_read_b64_tr_b16 v[210:211], v144 offset:7264
	s_waitcnt lgkmcnt(9)
	v_mfma_f32_16x16x32_bf16 v[92:95], v[236:239], v[200:203], v[80:83]
	ds_read2_b32 v[212:213], v161 offset1:1
	ds_read2_b32 v[214:215], v160 offset1:1
	s_nop 2
	s_waitcnt lgkmcnt(9)
	v_pk_mul_f32 v[72:73], v[72:73], v[244:245]
	s_waitcnt lgkmcnt(8)
	v_pk_mul_f32 v[74:75], v[74:75], v[246:247]
	s_nop 1
	v_mfma_f32_16x16x32_bf16 v[72:75], v[240:243], v[200:203], v[72:75]
	s_waitcnt lgkmcnt(5)
	v_pk_mul_f32 v[76:77], v[76:77], v[204:205]
	s_waitcnt lgkmcnt(4)
	v_pk_mul_f32 v[78:79], v[78:79], v[206:207]
	s_nop 1
	v_mfma_f32_16x16x32_bf16 v[80:83], v[248:251], v[200:203], v[76:79]
	s_nop 2
	s_waitcnt vmcnt(11)
	ds_write_b128 v121, v[60:63] offset:32512
	s_waitcnt vmcnt(10)
	ds_write_b128 v122, v[68:71] offset:20736
	s_waitcnt lgkmcnt(3)
	v_pk_mul_f32 v[84:85], v[84:85], v[212:213]
	s_waitcnt lgkmcnt(2)
	v_pk_mul_f32 v[86:87], v[86:87], v[214:215]
	s_nop 1
	v_mfma_f32_16x16x32_bf16 v[88:91], v[208:211], v[200:203], v[84:87]
	s_waitcnt lgkmcnt(0)
	s_and_saveexec_b64 s[36:37], s[38:39]
	ds_write_b128 v148, v[64:67] offset:20736
	s_or_b64 exec, exec, s[36:37]
	s_and_saveexec_b64 s[36:37], s[40:41]
	ds_write_b32 v149, v120 offset:40704
	s_or_b64 exec, exec, s[36:37]
	s_cmp_gt_u32 s24, 60
	s_waitcnt lgkmcnt(0)
	s_barrier
	s_cbranch_scc1 .LBB0_579
	v_add_u32_e32 v60, 0x120, v150
	s_movk_i32 s2, 0x100
	v_cmp_gt_i32_e32 vcc, s2, v60
	v_add_u32_e32 v61, 32, v150
	v_mov_b32_e32 v63, s22
	v_cndmask_b32_e32 v62, v174, v175, vcc
	v_add3_u32 v62, v132, v62, s27
	v_cndmask_b32_e32 v60, v61, v60, vcc
	v_mov_b32_e32 v61, s21
	v_add_u32_e32 v62, 0xfffff641, v62
	v_cndmask_b32_e32 v61, v61, v63, vcc
	v_cndmask_b32_e64 v60, v62, v60, s[0:1]
	v_add_u32_e32 v60, v60, v61
	s_movk_i32 s2, 0x3800
	v_add_co_u32_e32 v68, vcc, 0xb000, v112
	v_mad_i64_i32 v[60:61], s[2:3], v60, s2, v[104:105]
	s_nop 0
	v_addc_co_u32_e32 v69, vcc, 0, v113, vcc
	global_load_dwordx4 v[60:63], v[60:61], off offset:1024
	s_nop 0
	global_load_dwordx4 v[68:71], v[68:69], off nt
	s_and_saveexec_b64 s[36:37], s[38:39]
	s_cbranch_execz .LBB0_637
	v_lshl_add_u64 v[64:65], v[106:107], 0, s[44:45]
	v_add_co_u32_e32 v64, vcc, 0x12841000, v64
	s_nop 1
	v_addc_co_u32_e32 v65, vcc, 0, v65, vcc
	global_load_dwordx4 v[64:67], v[64:65], off offset:2048 nt
